# GU2 SwiGLU epilogue: the 8 row-scale loads issued together with one wait (were fully serialized); on top of GU1 epilogue + logf loop rewrites
# baseline (speedup 1.0000x reference)
; __device__ __forceinline__ float rstd_of(u64 ss) { return rsqrtf((float)ss * (1.0f / 4294967296.0f) * (1.0f / DM) + EPS); }
;     __device__ __forceinline__ void operator()(const f32x4 (&acc)[2][2][4][2], const pg8::Unit& u, int wr, int wc, int fr, int fq) const {
;         const int row0 = u.pm * 256 + wr * 64 + fr, col0 = u.pn * 128 + wc * 32 + 8 * fq;
;         float rsv[2][4];
; #pragma unroll
;         for (int ai = 0; ai < 2; ++ai)
; #pragma unroll
;             for (int m = 0; m < 4; ++m) rsv[ai][m] = rstd_of(ss[row0 + ai * 128 + m * 16]);
;         __builtin_amdgcn_sched_barrier(0);
.LBB0_927:
	v_lshl_add_u32 v142, s6, 8, v149
	v_ashrrev_i32_e32 v143, 31, v142
	v_lshl_add_u64 v[162:163], v[142:143], 3, s[0:1]
	global_load_dwordx2 v[166:167], v[162:163], off
	global_load_dwordx2 v[168:169], v[162:163], off offset:128
	global_load_dwordx2 v[170:171], v[162:163], off offset:256
	global_load_dwordx2 v[172:173], v[162:163], off offset:384
	global_load_dwordx2 v[174:175], v[162:163], off offset:1024
	global_load_dwordx2 v[176:177], v[162:163], off offset:1152
	global_load_dwordx2 v[178:179], v[162:163], off offset:1280
	global_load_dwordx2 v[180:181], v[162:163], off offset:1408
	v_or_b32_e32 v144, 16, v142
	v_or_b32_e32 v146, 32, v142
	v_lshl_or_b32 v164, s2, 7, v153
	v_or_b32_e32 v140, 48, v142
	v_add_u32_e32 v141, 0x80, v142
	v_add_u32_e32 v145, 0x90, v142
	v_add_u32_e32 v143, 0xa0, v142
	v_add_u32_e32 v147, 0xb0, v142
	s_waitcnt vmcnt(0)
	v_ffbh_u32_e32 v182, v167
	v_ffbh_u32_e32 v183, v169
	v_ffbh_u32_e32 v184, v171
	v_ffbh_u32_e32 v185, v173
	v_ffbh_u32_e32 v186, v175
	v_ffbh_u32_e32 v187, v177
	v_ffbh_u32_e32 v188, v179
	v_ffbh_u32_e32 v189, v181
	v_min_u32_e32 v182, 32, v182
	v_min_u32_e32 v183, 32, v183
	v_min_u32_e32 v184, 32, v184
	v_min_u32_e32 v185, 32, v185
	v_min_u32_e32 v186, 32, v186
	v_min_u32_e32 v187, 32, v187
	v_min_u32_e32 v188, 32, v188
	v_min_u32_e32 v189, 32, v189
	v_lshlrev_b64 v[166:167], v182, v[166:167]
	v_lshlrev_b64 v[168:169], v183, v[168:169]
	v_lshlrev_b64 v[170:171], v184, v[170:171]
	v_lshlrev_b64 v[172:173], v185, v[172:173]
	v_lshlrev_b64 v[174:175], v186, v[174:175]
	v_lshlrev_b64 v[176:177], v187, v[176:177]
	v_lshlrev_b64 v[178:179], v188, v[178:179]
	v_lshlrev_b64 v[180:181], v189, v[180:181]
	v_min_u32_e32 v190, 1, v166
	v_min_u32_e32 v191, 1, v168
	v_min_u32_e32 v192, 1, v170
	v_min_u32_e32 v193, 1, v172
	v_min_u32_e32 v194, 1, v174
	v_min_u32_e32 v195, 1, v176
	v_min_u32_e32 v196, 1, v178
	v_min_u32_e32 v197, 1, v180
	v_or_b32_e32 v190, v167, v190
	v_or_b32_e32 v191, v169, v191
	v_or_b32_e32 v192, v171, v192
	v_or_b32_e32 v193, v173, v193
	v_or_b32_e32 v194, v175, v194
	v_or_b32_e32 v195, v177, v195
	v_or_b32_e32 v196, v179, v196
	v_or_b32_e32 v197, v181, v197
	v_cvt_f32_u32_e32 v190, v190
	v_cvt_f32_u32_e32 v191, v191
	v_cvt_f32_u32_e32 v192, v192
	v_cvt_f32_u32_e32 v193, v193
	v_cvt_f32_u32_e32 v194, v194
	v_cvt_f32_u32_e32 v195, v195
	v_cvt_f32_u32_e32 v196, v196
	v_cvt_f32_u32_e32 v197, v197
	v_sub_u32_e32 v182, 32, v182
	v_sub_u32_e32 v183, 32, v183
	v_sub_u32_e32 v184, 32, v184
	v_sub_u32_e32 v185, 32, v185
	v_sub_u32_e32 v186, 32, v186
	v_sub_u32_e32 v187, 32, v187
	v_sub_u32_e32 v188, 32, v188
	v_sub_u32_e32 v189, 32, v189
	v_ldexp_f32 v190, v190, v182
	v_ldexp_f32 v191, v191, v183
	v_ldexp_f32 v192, v192, v184
	v_ldexp_f32 v193, v193, v185
	v_ldexp_f32 v194, v194, v186
	v_ldexp_f32 v195, v195, v187
	v_ldexp_f32 v196, v196, v188
	v_ldexp_f32 v197, v197, v189
	v_mul_f32_e32 v190, 0x2f800000, v190
	v_mul_f32_e32 v191, 0x2f800000, v191
	v_mul_f32_e32 v192, 0x2f800000, v192
	v_mul_f32_e32 v193, 0x2f800000, v193
	v_mul_f32_e32 v194, 0x2f800000, v194
	v_mul_f32_e32 v195, 0x2f800000, v195
	v_mul_f32_e32 v196, 0x2f800000, v196
	v_mul_f32_e32 v197, 0x2f800000, v197
	v_fmamk_f32 v190, v190, 0x3a000000, v238
	v_fmamk_f32 v191, v191, 0x3a000000, v238
	v_fmamk_f32 v192, v192, 0x3a000000, v238
	v_fmamk_f32 v193, v193, 0x3a000000, v238
	v_fmamk_f32 v194, v194, 0x3a000000, v238
	v_fmamk_f32 v195, v195, 0x3a000000, v238
	v_fmamk_f32 v196, v196, 0x3a000000, v238
	v_fmamk_f32 v197, v197, 0x3a000000, v238
	v_cmp_gt_f32_e32 vcc, s34, v190
	v_mul_f32_e32 v182, 0x4b800000, v190
	s_nop 0
	v_cndmask_b32_e32 v190, v190, v182, vcc
	v_rsq_f32_e32 v190, v190
	s_nop 0
	v_mul_f32_e32 v182, 0x45800000, v190
	v_cndmask_b32_e32 v152, v190, v182, vcc
	v_cmp_gt_f32_e32 vcc, s34, v191
	v_mul_f32_e32 v183, 0x4b800000, v191
	s_nop 0
	v_cndmask_b32_e32 v191, v191, v183, vcc
	v_rsq_f32_e32 v191, v191
	s_nop 0
	v_mul_f32_e32 v183, 0x45800000, v191
	v_cndmask_b32_e32 v150, v191, v183, vcc
	v_cmp_gt_f32_e32 vcc, s34, v192
	v_mul_f32_e32 v184, 0x4b800000, v192
	s_nop 0
	v_cndmask_b32_e32 v192, v192, v184, vcc
	v_rsq_f32_e32 v192, v192
	s_nop 0
	v_mul_f32_e32 v184, 0x45800000, v192
	v_cndmask_b32_e32 v154, v192, v184, vcc
	v_cmp_gt_f32_e32 vcc, s34, v193
	v_mul_f32_e32 v185, 0x4b800000, v193
	s_nop 0
	v_cndmask_b32_e32 v193, v193, v185, vcc
	v_rsq_f32_e32 v193, v193
	s_nop 0
	v_mul_f32_e32 v185, 0x45800000, v193
	v_cndmask_b32_e32 v148, v193, v185, vcc
	v_cmp_gt_f32_e32 vcc, s34, v194
	v_mul_f32_e32 v186, 0x4b800000, v194
	s_nop 0
	v_cndmask_b32_e32 v194, v194, v186, vcc
	v_rsq_f32_e32 v194, v194
	s_nop 0
	v_mul_f32_e32 v186, 0x45800000, v194
	v_cndmask_b32_e32 v158, v194, v186, vcc
	v_cmp_gt_f32_e32 vcc, s34, v195
	v_mul_f32_e32 v187, 0x4b800000, v195
	s_nop 0
	v_cndmask_b32_e32 v195, v195, v187, vcc
	v_rsq_f32_e32 v195, v195
	s_nop 0
	v_mul_f32_e32 v187, 0x45800000, v195
	v_cndmask_b32_e32 v156, v195, v187, vcc
	v_cmp_gt_f32_e32 vcc, s34, v196
	v_mul_f32_e32 v188, 0x4b800000, v196
	s_nop 0
	v_cndmask_b32_e32 v196, v196, v188, vcc
	v_rsq_f32_e32 v196, v196
	s_nop 0
	v_mul_f32_e32 v188, 0x45800000, v196
	v_cndmask_b32_e32 v160, v196, v188, vcc
	v_cmp_gt_f32_e32 vcc, s34, v197
	v_mul_f32_e32 v189, 0x4b800000, v197
	s_nop 0
	v_cndmask_b32_e32 v197, v197, v189, vcc
	v_rsq_f32_e32 v197, v197
	s_nop 0
	v_mul_f32_e32 v189, 0x45800000, v197
	v_cndmask_b32_e32 v162, v197, v189, vcc
	v_pk_mul_f32 v[126:127], v[126:127], v[152:153] op_sel_hi:[1,0]
	v_pk_mul_f32 v[122:123], v[122:123], v[152:153] op_sel_hi:[1,0]
	v_mul_f32_e32 v157, 0xbfb8aa3b, v126
	v_exp_f32_e32 v166, v157
	v_mul_f32_e32 v157, 0xbfb8aa3b, v122
; __device__ __forceinline__ unsigned cvt_pk_bf16(float lo, float hi) { unsigned r; asm volatile("v_cvt_pk_bf16_f32 %0, %1, %2" : "=v"(r) : "v"(lo), "v"(hi)); return r; }
;     __device__ __forceinline__ void operator()(const f32x4 (&acc)[2][2][4][2], const pg8::Unit& u, int wr, int wc, int fr, int fq) const {
;     ...
;                 const int row = row0 + ai * 128 + m * 16; const float rs = rsv[ai][m];
;                 const f32x4 g0 = acc[ai][0][m][0] * rs, g1 = acc[ai][0][m][1] * rs, u0 = acc[ai][1][m][0] * rs, u1 = acc[ai][1][m][1] * rs;
;                 const f32x4 t0 = g0 * (-LOG2E), t1 = g1 * (-LOG2E);
;                 f32x4 e0, e1;
; #pragma unroll
;                 for (int e = 0; e < 4; ++e) { e0[e] = __builtin_amdgcn_exp2f(t0[e]); e1[e] = __builtin_amdgcn_exp2f(t1[e]); }
;                 e0 = e0 + 1.0f; e1 = e1 + 1.0f;
;                 f32x4 r0, r1;
; #pragma unroll
;                 for (int e = 0; e < 4; ++e) { r0[e] = __builtin_amdgcn_rcpf(e0[e]); r1[e] = __builtin_amdgcn_rcpf(e1[e]); }
;                 const f32x4 o0 = (g0 * r0) * u0, o1 = (g1 * r1) * u1;
;                 u32x4 w; w.x = pg8::cvt_pk_bf16(o0[0], o0[1]); w.y = pg8::cvt_pk_bf16(o0[2], o0[3]); w.z = pg8::cvt_pk_bf16(o1[0], o1[1]); w.w = pg8::cvt_pk_bf16(o1[2], o1[3]);
;                 *(u32x4*)(act + (size_t)row * DFF + col0) = w;
	v_exp_f32_e32 v168, v157
	v_mul_f32_e32 v157, 0xbfb8aa3b, v127
	v_pk_mul_f32 v[128:129], v[128:129], v[152:153] op_sel_hi:[1,0]
	v_exp_f32_e32 v167, v157
	v_mul_f32_e32 v157, 0xbfb8aa3b, v123
	v_pk_mul_f32 v[124:125], v[124:125], v[152:153] op_sel_hi:[1,0]
	v_exp_f32_e32 v169, v157
	v_mul_f32_e32 v157, 0xbfb8aa3b, v128
	v_exp_f32_e32 v170, v157
	v_mul_f32_e32 v157, 0xbfb8aa3b, v124
	v_exp_f32_e32 v172, v157
	v_mul_f32_e32 v157, 0xbfb8aa3b, v129
	v_exp_f32_e32 v171, v157
	v_mul_f32_e32 v157, 0xbfb8aa3b, v125
	v_exp_f32_e32 v173, v157
	v_pk_add_f32 v[166:167], v[166:167], 1.0 op_sel_hi:[1,0]
	v_pk_add_f32 v[170:171], v[170:171], 1.0 op_sel_hi:[1,0]
	v_pk_add_f32 v[168:169], v[168:169], 1.0 op_sel_hi:[1,0]
	v_pk_add_f32 v[172:173], v[172:173], 1.0 op_sel_hi:[1,0]
	v_rcp_f32_e32 v166, v166
	v_rcp_f32_e32 v168, v168
	v_rcp_f32_e32 v167, v167
	v_rcp_f32_e32 v169, v169
	v_rcp_f32_e32 v170, v170
	v_rcp_f32_e32 v171, v171
	v_rcp_f32_e32 v172, v172
	v_rcp_f32_e32 v173, v173
	v_pk_mul_f32 v[118:119], v[118:119], v[152:153] op_sel_hi:[1,0]
	v_pk_mul_f32 v[120:121], v[120:121], v[152:153] op_sel_hi:[1,0]
	v_pk_mul_f32 v[114:115], v[114:115], v[152:153] op_sel_hi:[1,0]
	v_pk_mul_f32 v[126:127], v[126:127], v[166:167]
	v_pk_mul_f32 v[128:129], v[128:129], v[170:171]
	v_pk_mul_f32 v[122:123], v[122:123], v[168:169]
	v_pk_mul_f32 v[116:117], v[116:117], v[152:153] op_sel_hi:[1,0]
	v_pk_mul_f32 v[120:121], v[120:121], v[128:129]
	v_pk_mul_f32 v[118:119], v[118:119], v[126:127]
	v_pk_mul_f32 v[124:125], v[124:125], v[172:173]
	v_pk_mul_f32 v[114:115], v[114:115], v[122:123]
	v_ashrrev_i32_e32 v165, 31, v164
	v_pk_mul_f32 v[116:117], v[116:117], v[124:125]
	v_cvt_pk_bf16_f32 v118, v118, v119
	v_cvt_pk_bf16_f32 v119, v120, v121
	v_cvt_pk_bf16_f32 v120, v114, v115
	v_mov_b64_e32 v[114:115], s[62:63]
	v_cvt_pk_bf16_f32 v121, v116, v117
	v_mad_i64_i32 v[122:123], s[6:7], v142, s59, v[114:115]
	v_lshlrev_b64 v[116:117], 1, v[164:165]
	v_lshl_add_u64 v[122:123], v[122:123], 0, v[116:117]
	v_pk_mul_f32 v[106:107], v[106:107], v[150:151] op_sel_hi:[1,0]
	global_store_dwordx4 v[122:123], v[118:121], off
	v_pk_mul_f32 v[110:111], v[110:111], v[150:151] op_sel_hi:[1,0]
	v_pk_mul_f32 v[108:109], v[108:109], v[150:151] op_sel_hi:[1,0]
	v_mul_f32_e32 v119, 0xbfb8aa3b, v106
	v_mul_f32_e32 v118, 0xbfb8aa3b, v110
	v_exp_f32_e32 v120, v119
	v_mul_f32_e32 v119, 0xbfb8aa3b, v111
	v_pk_mul_f32 v[112:113], v[112:113], v[150:151] op_sel_hi:[1,0]
	v_exp_f32_e32 v118, v118
	v_exp_f32_e32 v119, v119
	v_mul_f32_e32 v121, 0xbfb8aa3b, v107
	v_mul_f32_e32 v123, 0xbfb8aa3b, v108
	v_mul_f32_e32 v125, 0xbfb8aa3b, v109
	v_exp_f32_e32 v121, v121
	v_mul_f32_e32 v122, 0xbfb8aa3b, v112
	v_exp_f32_e32 v124, v123
	v_mul_f32_e32 v123, 0xbfb8aa3b, v113
	v_exp_f32_e32 v125, v125
	v_exp_f32_e32 v122, v122
	v_exp_f32_e32 v123, v123
	v_pk_add_f32 v[118:119], v[118:119], 1.0 op_sel_hi:[1,0]
	v_pk_add_f32 v[124:125], v[124:125], 1.0 op_sel_hi:[1,0]
	v_pk_add_f32 v[120:121], v[120:121], 1.0 op_sel_hi:[1,0]
	v_rcp_f32_e32 v118, v118
	v_rcp_f32_e32 v119, v119
	v_pk_add_f32 v[122:123], v[122:123], 1.0 op_sel_hi:[1,0]
	v_rcp_f32_e32 v120, v120
	v_rcp_f32_e32 v121, v121
	v_rcp_f32_e32 v124, v124
	v_rcp_f32_e32 v125, v125
	v_rcp_f32_e32 v122, v122
	v_rcp_f32_e32 v123, v123
	v_pk_mul_f32 v[102:103], v[102:103], v[150:151] op_sel_hi:[1,0]
	v_pk_mul_f32 v[110:111], v[110:111], v[118:119]
	v_pk_mul_f32 v[98:99], v[98:99], v[150:151] op_sel_hi:[1,0]
	v_pk_mul_f32 v[100:101], v[100:101], v[150:151] op_sel_hi:[1,0]
	v_pk_mul_f32 v[102:103], v[102:103], v[110:111]
	v_pk_mul_f32 v[106:107], v[106:107], v[120:121]
	v_pk_mul_f32 v[108:109], v[108:109], v[124:125]
	v_pk_mul_f32 v[104:105], v[104:105], v[150:151] op_sel_hi:[1,0]
	v_pk_mul_f32 v[112:113], v[112:113], v[122:123]
	v_pk_mul_f32 v[108:109], v[100:101], v[108:109]
	v_pk_mul_f32 v[100:101], v[98:99], v[106:107]
	v_cvt_pk_bf16_f32 v98, v102, v103
	v_mad_i64_i32 v[102:103], s[6:7], v144, s59, v[114:115]
	v_pk_mul_f32 v[104:105], v[104:105], v[112:113]
	v_lshl_add_u64 v[102:103], v[102:103], 0, v[116:117]
	v_cvt_pk_bf16_f32 v99, v104, v105
	v_pk_mul_f32 v[90:91], v[90:91], v[154:155] op_sel_hi:[1,0]
	v_cvt_pk_bf16_f32 v100, v100, v101
	v_cvt_pk_bf16_f32 v101, v108, v109
	global_store_dwordx4 v[102:103], v[98:101], off
	v_pk_mul_f32 v[94:95], v[94:95], v[154:155] op_sel_hi:[1,0]
	v_pk_mul_f32 v[92:93], v[92:93], v[154:155] op_sel_hi:[1,0]
	v_mul_f32_e32 v99, 0xbfb8aa3b, v90
	v_mul_f32_e32 v98, 0xbfb8aa3b, v94
	v_exp_f32_e32 v100, v99
	v_mul_f32_e32 v99, 0xbfb8aa3b, v95
	v_pk_mul_f32 v[96:97], v[96:97], v[154:155] op_sel_hi:[1,0]
	v_exp_f32_e32 v98, v98
	v_exp_f32_e32 v99, v99
	v_mul_f32_e32 v101, 0xbfb8aa3b, v91
	v_mul_f32_e32 v103, 0xbfb8aa3b, v92
	v_mul_f32_e32 v105, 0xbfb8aa3b, v93
	v_exp_f32_e32 v101, v101
	v_mul_f32_e32 v102, 0xbfb8aa3b, v96
	v_exp_f32_e32 v104, v103
	v_mul_f32_e32 v103, 0xbfb8aa3b, v97
	v_exp_f32_e32 v105, v105
	v_exp_f32_e32 v102, v102
	v_exp_f32_e32 v103, v103
	v_pk_add_f32 v[98:99], v[98:99], 1.0 op_sel_hi:[1,0]
	v_pk_add_f32 v[104:105], v[104:105], 1.0 op_sel_hi:[1,0]
	v_pk_add_f32 v[100:101], v[100:101], 1.0 op_sel_hi:[1,0]
	v_rcp_f32_e32 v98, v98
	v_rcp_f32_e32 v99, v99
	v_pk_add_f32 v[102:103], v[102:103], 1.0 op_sel_hi:[1,0]
	v_rcp_f32_e32 v100, v100
	v_rcp_f32_e32 v101, v101
	v_rcp_f32_e32 v104, v104
	v_rcp_f32_e32 v105, v105
	v_rcp_f32_e32 v102, v102
	v_rcp_f32_e32 v103, v103
	v_pk_mul_f32 v[86:87], v[86:87], v[154:155] op_sel_hi:[1,0]
	v_pk_mul_f32 v[94:95], v[94:95], v[98:99]
	v_pk_mul_f32 v[82:83], v[82:83], v[154:155] op_sel_hi:[1,0]
	v_pk_mul_f32 v[84:85], v[84:85], v[154:155] op_sel_hi:[1,0]
	v_pk_mul_f32 v[86:87], v[86:87], v[94:95]
; __device__ __forceinline__ unsigned cvt_pk_bf16(float lo, float hi) { unsigned r; asm volatile("v_cvt_pk_bf16_f32 %0, %1, %2" : "=v"(r) : "v"(lo), "v"(hi)); return r; }
;     __device__ __forceinline__ void operator()(const f32x4 (&acc)[2][2][4][2], const pg8::Unit& u, int wr, int wc, int fr, int fq) const {
;     ...
;                 const int row = row0 + ai * 128 + m * 16; const float rs = rsv[ai][m];
;                 const f32x4 g0 = acc[ai][0][m][0] * rs, g1 = acc[ai][0][m][1] * rs, u0 = acc[ai][1][m][0] * rs, u1 = acc[ai][1][m][1] * rs;
;                 const f32x4 t0 = g0 * (-LOG2E), t1 = g1 * (-LOG2E);
;                 f32x4 e0, e1;
; #pragma unroll
;                 for (int e = 0; e < 4; ++e) { e0[e] = __builtin_amdgcn_exp2f(t0[e]); e1[e] = __builtin_amdgcn_exp2f(t1[e]); }
;                 e0 = e0 + 1.0f; e1 = e1 + 1.0f;
;                 f32x4 r0, r1;
; #pragma unroll
;                 for (int e = 0; e < 4; ++e) { r0[e] = __builtin_amdgcn_rcpf(e0[e]); r1[e] = __builtin_amdgcn_rcpf(e1[e]); }
;                 const f32x4 o0 = (g0 * r0) * u0, o1 = (g1 * r1) * u1;
;                 u32x4 w; w.x = pg8::cvt_pk_bf16(o0[0], o0[1]); w.y = pg8::cvt_pk_bf16(o0[2], o0[3]); w.z = pg8::cvt_pk_bf16(o1[0], o1[1]); w.w = pg8::cvt_pk_bf16(o1[2], o1[3]);
;                 *(u32x4*)(act + (size_t)row * DFF + col0) = w;
	v_pk_mul_f32 v[90:91], v[90:91], v[100:101]
	v_pk_mul_f32 v[92:93], v[92:93], v[104:105]
	v_pk_mul_f32 v[88:89], v[88:89], v[154:155] op_sel_hi:[1,0]
	v_pk_mul_f32 v[96:97], v[96:97], v[102:103]
	v_pk_mul_f32 v[92:93], v[84:85], v[92:93]
	v_pk_mul_f32 v[84:85], v[82:83], v[90:91]
	v_cvt_pk_bf16_f32 v82, v86, v87
	v_mad_i64_i32 v[86:87], s[6:7], v146, s59, v[114:115]
	v_pk_mul_f32 v[88:89], v[88:89], v[96:97]
	v_lshl_add_u64 v[86:87], v[86:87], 0, v[116:117]
	v_cvt_pk_bf16_f32 v83, v88, v89
	v_pk_mul_f32 v[74:75], v[74:75], v[148:149] op_sel_hi:[1,0]
	v_cvt_pk_bf16_f32 v84, v84, v85
	v_cvt_pk_bf16_f32 v85, v92, v93
	global_store_dwordx4 v[86:87], v[82:85], off
	v_pk_mul_f32 v[78:79], v[78:79], v[148:149] op_sel_hi:[1,0]
	v_pk_mul_f32 v[76:77], v[76:77], v[148:149] op_sel_hi:[1,0]
	v_mul_f32_e32 v83, 0xbfb8aa3b, v74
	v_mul_f32_e32 v82, 0xbfb8aa3b, v78
	v_exp_f32_e32 v84, v83
	v_mul_f32_e32 v83, 0xbfb8aa3b, v79
	v_pk_mul_f32 v[80:81], v[80:81], v[148:149] op_sel_hi:[1,0]
	v_exp_f32_e32 v82, v82
	v_exp_f32_e32 v83, v83
	v_mul_f32_e32 v85, 0xbfb8aa3b, v75
	v_mul_f32_e32 v87, 0xbfb8aa3b, v76
	v_mul_f32_e32 v89, 0xbfb8aa3b, v77
	v_exp_f32_e32 v85, v85
	v_mul_f32_e32 v86, 0xbfb8aa3b, v80
	v_exp_f32_e32 v88, v87
	v_mul_f32_e32 v87, 0xbfb8aa3b, v81
	v_exp_f32_e32 v89, v89
	v_exp_f32_e32 v86, v86
	v_exp_f32_e32 v87, v87
	v_pk_add_f32 v[82:83], v[82:83], 1.0 op_sel_hi:[1,0]
	v_pk_add_f32 v[88:89], v[88:89], 1.0 op_sel_hi:[1,0]
	v_pk_add_f32 v[84:85], v[84:85], 1.0 op_sel_hi:[1,0]
	v_rcp_f32_e32 v82, v82
	v_rcp_f32_e32 v83, v83
	v_pk_add_f32 v[86:87], v[86:87], 1.0 op_sel_hi:[1,0]
	v_rcp_f32_e32 v84, v84
	v_rcp_f32_e32 v85, v85
	v_rcp_f32_e32 v88, v88
	v_rcp_f32_e32 v89, v89
	v_rcp_f32_e32 v86, v86
	v_rcp_f32_e32 v87, v87
	v_pk_mul_f32 v[70:71], v[70:71], v[148:149] op_sel_hi:[1,0]
	v_pk_mul_f32 v[78:79], v[78:79], v[82:83]
	v_pk_mul_f32 v[66:67], v[66:67], v[148:149] op_sel_hi:[1,0]
	v_pk_mul_f32 v[68:69], v[68:69], v[148:149] op_sel_hi:[1,0]
	v_pk_mul_f32 v[70:71], v[70:71], v[78:79]
	v_pk_mul_f32 v[74:75], v[74:75], v[84:85]
	v_pk_mul_f32 v[76:77], v[76:77], v[88:89]
	v_pk_mul_f32 v[72:73], v[72:73], v[148:149] op_sel_hi:[1,0]
	v_pk_mul_f32 v[80:81], v[80:81], v[86:87]
	v_pk_mul_f32 v[76:77], v[68:69], v[76:77]
	v_pk_mul_f32 v[68:69], v[66:67], v[74:75]
	v_cvt_pk_bf16_f32 v66, v70, v71
	v_mad_i64_i32 v[70:71], s[6:7], v140, s59, v[114:115]
	v_pk_mul_f32 v[72:73], v[72:73], v[80:81]
	v_lshl_add_u64 v[70:71], v[70:71], 0, v[116:117]
	v_cvt_pk_bf16_f32 v67, v72, v73
	v_pk_mul_f32 v[58:59], v[58:59], v[158:159] op_sel_hi:[1,0]
	v_cvt_pk_bf16_f32 v68, v68, v69
	v_cvt_pk_bf16_f32 v69, v76, v77
	global_store_dwordx4 v[70:71], v[66:69], off
	v_pk_mul_f32 v[62:63], v[62:63], v[158:159] op_sel_hi:[1,0]
	v_pk_mul_f32 v[60:61], v[60:61], v[158:159] op_sel_hi:[1,0]
	v_mul_f32_e32 v67, 0xbfb8aa3b, v58
	v_mul_f32_e32 v66, 0xbfb8aa3b, v62
	v_exp_f32_e32 v68, v67
	v_mul_f32_e32 v67, 0xbfb8aa3b, v63
	v_pk_mul_f32 v[64:65], v[64:65], v[158:159] op_sel_hi:[1,0]
	v_exp_f32_e32 v66, v66
	v_exp_f32_e32 v67, v67
	v_mul_f32_e32 v69, 0xbfb8aa3b, v59
	v_mul_f32_e32 v71, 0xbfb8aa3b, v60
	v_mul_f32_e32 v73, 0xbfb8aa3b, v61
	v_exp_f32_e32 v69, v69
	v_mul_f32_e32 v70, 0xbfb8aa3b, v64
	v_exp_f32_e32 v72, v71
	v_mul_f32_e32 v71, 0xbfb8aa3b, v65
	v_exp_f32_e32 v73, v73
	v_exp_f32_e32 v70, v70
	v_exp_f32_e32 v71, v71
	v_pk_add_f32 v[66:67], v[66:67], 1.0 op_sel_hi:[1,0]
	v_pk_add_f32 v[72:73], v[72:73], 1.0 op_sel_hi:[1,0]
	v_pk_add_f32 v[68:69], v[68:69], 1.0 op_sel_hi:[1,0]
	v_rcp_f32_e32 v66, v66
	v_rcp_f32_e32 v67, v67
	v_pk_add_f32 v[70:71], v[70:71], 1.0 op_sel_hi:[1,0]
	v_rcp_f32_e32 v68, v68
	v_rcp_f32_e32 v69, v69
	v_rcp_f32_e32 v72, v72
	v_rcp_f32_e32 v73, v73
	v_rcp_f32_e32 v70, v70
	v_rcp_f32_e32 v71, v71
	v_pk_mul_f32 v[54:55], v[54:55], v[158:159] op_sel_hi:[1,0]
	v_pk_mul_f32 v[62:63], v[62:63], v[66:67]
	v_pk_mul_f32 v[50:51], v[50:51], v[158:159] op_sel_hi:[1,0]
	v_pk_mul_f32 v[52:53], v[52:53], v[158:159] op_sel_hi:[1,0]
	v_pk_mul_f32 v[54:55], v[54:55], v[62:63]
	v_pk_mul_f32 v[58:59], v[58:59], v[68:69]
	v_pk_mul_f32 v[60:61], v[60:61], v[72:73]
	v_pk_mul_f32 v[56:57], v[56:57], v[158:159] op_sel_hi:[1,0]
	v_pk_mul_f32 v[64:65], v[64:65], v[70:71]
	v_pk_mul_f32 v[60:61], v[52:53], v[60:61]
	v_pk_mul_f32 v[52:53], v[50:51], v[58:59]
	v_cvt_pk_bf16_f32 v50, v54, v55
	v_mad_i64_i32 v[54:55], s[6:7], v141, s59, v[114:115]
	v_pk_mul_f32 v[56:57], v[56:57], v[64:65]
	v_lshl_add_u64 v[54:55], v[54:55], 0, v[116:117]
	v_cvt_pk_bf16_f32 v51, v56, v57
	v_pk_mul_f32 v[42:43], v[42:43], v[156:157] op_sel_hi:[1,0]
	v_cvt_pk_bf16_f32 v52, v52, v53
	v_cvt_pk_bf16_f32 v53, v60, v61
	global_store_dwordx4 v[54:55], v[50:53], off
	v_pk_mul_f32 v[46:47], v[46:47], v[156:157] op_sel_hi:[1,0]
	v_pk_mul_f32 v[44:45], v[44:45], v[156:157] op_sel_hi:[1,0]
	v_mul_f32_e32 v51, 0xbfb8aa3b, v42
	v_mul_f32_e32 v50, 0xbfb8aa3b, v46
	v_exp_f32_e32 v52, v51
	v_mul_f32_e32 v51, 0xbfb8aa3b, v47
	v_pk_mul_f32 v[48:49], v[48:49], v[156:157] op_sel_hi:[1,0]
	v_exp_f32_e32 v50, v50
	v_exp_f32_e32 v51, v51
	v_mul_f32_e32 v53, 0xbfb8aa3b, v43
	v_mul_f32_e32 v55, 0xbfb8aa3b, v44
	v_mul_f32_e32 v57, 0xbfb8aa3b, v45
	v_exp_f32_e32 v53, v53
	v_mul_f32_e32 v54, 0xbfb8aa3b, v48
	v_exp_f32_e32 v56, v55
	v_mul_f32_e32 v55, 0xbfb8aa3b, v49
	v_exp_f32_e32 v57, v57
	v_exp_f32_e32 v54, v54
	v_exp_f32_e32 v55, v55
	v_pk_add_f32 v[50:51], v[50:51], 1.0 op_sel_hi:[1,0]
; __device__ __forceinline__ unsigned cvt_pk_bf16(float lo, float hi) { unsigned r; asm volatile("v_cvt_pk_bf16_f32 %0, %1, %2" : "=v"(r) : "v"(lo), "v"(hi)); return r; }
; #define PG8_BAR __builtin_amdgcn_s_barrier()
; template <class Epi, class Sched, bool ALIGN_EPI = false, bool SP2 = false>
; __device__ __forceinline__ void gemm_phase(LAS unsigned char* lds, const Gemm g, const Sched& S, const Epi& E) {
;     ...
;         if constexpr (ALIGN_EPI) { if (wr == 0) PG8_BAR; }
;         E(acc, cur, wr, wc, fr, fq); S.done(cur);
;         if (!has_next) break;
; #pragma unroll
;         for (int a = 0; a < 2; ++a)
; #pragma unroll
;             for (int b = 0; b < 2; ++b)
; #pragma unroll
;                 for (int m = 0; m < 4; ++m)
; #pragma unroll
;                     for (int n = 0; n < 2; ++n) acc[a][b][m][n] = (f32x4){0.f, 0.f, 0.f, 0.f};
;         cur = nxt; cA = nA; cB = nB; ++ui;
;         if constexpr (ALIGN_EPI) { if (wr == 1) PG8_BAR; }
;     __device__ __forceinline__ void operator()(const f32x4 (&acc)[2][2][4][2], const pg8::Unit& u, int wr, int wc, int fr, int fq) const {
;     ...
;                 const int row = row0 + ai * 128 + m * 16; const float rs = rsv[ai][m];
;                 const f32x4 g0 = acc[ai][0][m][0] * rs, g1 = acc[ai][0][m][1] * rs, u0 = acc[ai][1][m][0] * rs, u1 = acc[ai][1][m][1] * rs;
;                 const f32x4 t0 = g0 * (-LOG2E), t1 = g1 * (-LOG2E);
;                 f32x4 e0, e1;
; #pragma unroll
;                 for (int e = 0; e < 4; ++e) { e0[e] = __builtin_amdgcn_exp2f(t0[e]); e1[e] = __builtin_amdgcn_exp2f(t1[e]); }
;                 e0 = e0 + 1.0f; e1 = e1 + 1.0f;
;                 f32x4 r0, r1;
; #pragma unroll
;                 for (int e = 0; e < 4; ++e) { r0[e] = __builtin_amdgcn_rcpf(e0[e]); r1[e] = __builtin_amdgcn_rcpf(e1[e]); }
;                 const f32x4 o0 = (g0 * r0) * u0, o1 = (g1 * r1) * u1;
;                 u32x4 w; w.x = pg8::cvt_pk_bf16(o0[0], o0[1]); w.y = pg8::cvt_pk_bf16(o0[2], o0[3]); w.z = pg8::cvt_pk_bf16(o1[0], o1[1]); w.w = pg8::cvt_pk_bf16(o1[2], o1[3]);
;                 *(u32x4*)(act + (size_t)row * DFF + col0) = w;
;             }
	v_pk_add_f32 v[56:57], v[56:57], 1.0 op_sel_hi:[1,0]
	v_pk_add_f32 v[52:53], v[52:53], 1.0 op_sel_hi:[1,0]
	v_rcp_f32_e32 v50, v50
	v_rcp_f32_e32 v51, v51
	v_pk_add_f32 v[54:55], v[54:55], 1.0 op_sel_hi:[1,0]
	v_rcp_f32_e32 v52, v52
	v_rcp_f32_e32 v53, v53
	v_rcp_f32_e32 v56, v56
	v_rcp_f32_e32 v57, v57
	v_rcp_f32_e32 v54, v54
	v_rcp_f32_e32 v55, v55
	v_pk_mul_f32 v[38:39], v[38:39], v[156:157] op_sel_hi:[1,0]
	v_pk_mul_f32 v[46:47], v[46:47], v[50:51]
	v_pk_mul_f32 v[34:35], v[34:35], v[156:157] op_sel_hi:[1,0]
	v_pk_mul_f32 v[36:37], v[36:37], v[156:157] op_sel_hi:[1,0]
	v_pk_mul_f32 v[38:39], v[38:39], v[46:47]
	v_pk_mul_f32 v[42:43], v[42:43], v[52:53]
	v_pk_mul_f32 v[44:45], v[44:45], v[56:57]
	v_pk_mul_f32 v[40:41], v[40:41], v[156:157] op_sel_hi:[1,0]
	v_pk_mul_f32 v[48:49], v[48:49], v[54:55]
	v_pk_mul_f32 v[44:45], v[36:37], v[44:45]
	v_pk_mul_f32 v[36:37], v[34:35], v[42:43]
	v_cvt_pk_bf16_f32 v34, v38, v39
	v_mad_i64_i32 v[38:39], s[6:7], v145, s59, v[114:115]
	v_pk_mul_f32 v[40:41], v[40:41], v[48:49]
	v_lshl_add_u64 v[38:39], v[38:39], 0, v[116:117]
	v_cvt_pk_bf16_f32 v35, v40, v41
	v_pk_mul_f32 v[26:27], v[26:27], v[160:161] op_sel_hi:[1,0]
	v_cvt_pk_bf16_f32 v36, v36, v37
	v_cvt_pk_bf16_f32 v37, v44, v45
	global_store_dwordx4 v[38:39], v[34:37], off
	v_pk_mul_f32 v[30:31], v[30:31], v[160:161] op_sel_hi:[1,0]
	v_pk_mul_f32 v[28:29], v[28:29], v[160:161] op_sel_hi:[1,0]
	v_mul_f32_e32 v35, 0xbfb8aa3b, v26
	v_mul_f32_e32 v34, 0xbfb8aa3b, v30
	v_exp_f32_e32 v36, v35
	v_mul_f32_e32 v35, 0xbfb8aa3b, v31
	v_pk_mul_f32 v[32:33], v[32:33], v[160:161] op_sel_hi:[1,0]
	v_exp_f32_e32 v34, v34
	v_exp_f32_e32 v35, v35
	v_mul_f32_e32 v37, 0xbfb8aa3b, v27
	v_mul_f32_e32 v39, 0xbfb8aa3b, v28
	v_mul_f32_e32 v41, 0xbfb8aa3b, v29
	v_exp_f32_e32 v37, v37
	v_mul_f32_e32 v38, 0xbfb8aa3b, v32
	v_exp_f32_e32 v40, v39
	v_mul_f32_e32 v39, 0xbfb8aa3b, v33
	v_exp_f32_e32 v41, v41
	v_exp_f32_e32 v38, v38
	v_exp_f32_e32 v39, v39
	v_pk_add_f32 v[34:35], v[34:35], 1.0 op_sel_hi:[1,0]
	v_pk_add_f32 v[40:41], v[40:41], 1.0 op_sel_hi:[1,0]
	v_pk_add_f32 v[36:37], v[36:37], 1.0 op_sel_hi:[1,0]
	v_rcp_f32_e32 v34, v34
	v_rcp_f32_e32 v35, v35
	v_pk_add_f32 v[38:39], v[38:39], 1.0 op_sel_hi:[1,0]
	v_rcp_f32_e32 v36, v36
	v_rcp_f32_e32 v37, v37
	v_rcp_f32_e32 v40, v40
	v_rcp_f32_e32 v41, v41
	v_rcp_f32_e32 v38, v38
	v_rcp_f32_e32 v39, v39
	v_pk_mul_f32 v[22:23], v[22:23], v[160:161] op_sel_hi:[1,0]
	v_pk_mul_f32 v[30:31], v[30:31], v[34:35]
	v_pk_mul_f32 v[18:19], v[18:19], v[160:161] op_sel_hi:[1,0]
	v_pk_mul_f32 v[20:21], v[20:21], v[160:161] op_sel_hi:[1,0]
	v_pk_mul_f32 v[22:23], v[22:23], v[30:31]
	v_pk_mul_f32 v[26:27], v[26:27], v[36:37]
	v_pk_mul_f32 v[28:29], v[28:29], v[40:41]
	v_pk_mul_f32 v[24:25], v[24:25], v[160:161] op_sel_hi:[1,0]
	v_pk_mul_f32 v[32:33], v[32:33], v[38:39]
	v_pk_mul_f32 v[28:29], v[20:21], v[28:29]
	v_pk_mul_f32 v[20:21], v[18:19], v[26:27]
	v_cvt_pk_bf16_f32 v18, v22, v23
	v_mad_i64_i32 v[22:23], s[6:7], v143, s59, v[114:115]
	v_pk_mul_f32 v[24:25], v[24:25], v[32:33]
	v_lshl_add_u64 v[22:23], v[22:23], 0, v[116:117]
	v_cvt_pk_bf16_f32 v19, v24, v25
	v_pk_mul_f32 v[10:11], v[10:11], v[162:163] op_sel_hi:[1,0]
	v_cvt_pk_bf16_f32 v20, v20, v21
	v_cvt_pk_bf16_f32 v21, v28, v29
	global_store_dwordx4 v[22:23], v[18:21], off
	v_pk_mul_f32 v[14:15], v[14:15], v[162:163] op_sel_hi:[1,0]
	v_pk_mul_f32 v[12:13], v[12:13], v[162:163] op_sel_hi:[1,0]
	v_mul_f32_e32 v19, 0xbfb8aa3b, v10
	v_mul_f32_e32 v18, 0xbfb8aa3b, v14
	v_exp_f32_e32 v20, v19
	v_mul_f32_e32 v19, 0xbfb8aa3b, v15
	v_exp_f32_e32 v18, v18
	v_exp_f32_e32 v19, v19
	v_mul_f32_e32 v21, 0xbfb8aa3b, v11
	v_mul_f32_e32 v23, 0xbfb8aa3b, v12
	v_mul_f32_e32 v25, 0xbfb8aa3b, v13
	v_pk_mul_f32 v[16:17], v[16:17], v[162:163] op_sel_hi:[1,0]
	v_exp_f32_e32 v21, v21
	v_exp_f32_e32 v24, v23
	v_exp_f32_e32 v25, v25
	v_mul_f32_e32 v22, 0xbfb8aa3b, v16
	v_mul_f32_e32 v23, 0xbfb8aa3b, v17
	v_exp_f32_e32 v22, v22
	v_exp_f32_e32 v23, v23
	v_pk_add_f32 v[18:19], v[18:19], 1.0 op_sel_hi:[1,0]
	v_pk_add_f32 v[24:25], v[24:25], 1.0 op_sel_hi:[1,0]
	v_pk_add_f32 v[20:21], v[20:21], 1.0 op_sel_hi:[1,0]
	v_rcp_f32_e32 v18, v18
	v_rcp_f32_e32 v19, v19
	v_rcp_f32_e32 v20, v20
	v_rcp_f32_e32 v21, v21
	v_rcp_f32_e32 v24, v24
	v_rcp_f32_e32 v25, v25
	v_pk_add_f32 v[22:23], v[22:23], 1.0 op_sel_hi:[1,0]
	v_pk_mul_f32 v[6:7], v[6:7], v[162:163] op_sel_hi:[1,0]
	v_rcp_f32_e32 v22, v22
	v_rcp_f32_e32 v23, v23
	v_pk_mul_f32 v[14:15], v[14:15], v[18:19]
	v_pk_mul_f32 v[2:3], v[2:3], v[162:163] op_sel_hi:[1,0]
	v_pk_mul_f32 v[4:5], v[4:5], v[162:163] op_sel_hi:[1,0]
	v_pk_mul_f32 v[6:7], v[6:7], v[14:15]
	v_pk_mul_f32 v[10:11], v[10:11], v[20:21]
	v_pk_mul_f32 v[12:13], v[12:13], v[24:25]
	v_pk_mul_f32 v[8:9], v[8:9], v[162:163] op_sel_hi:[1,0]
	v_pk_mul_f32 v[12:13], v[4:5], v[12:13]
	v_pk_mul_f32 v[4:5], v[2:3], v[10:11]
	v_cvt_pk_bf16_f32 v2, v6, v7
	v_mad_i64_i32 v[6:7], s[6:7], v147, s59, v[114:115]
	v_pk_mul_f32 v[16:17], v[16:17], v[22:23]
	v_lshl_add_u64 v[6:7], v[6:7], 0, v[116:117]
	s_andn2_b64 vcc, exec, s[38:39]
	s_mov_b64 s[26:27], -1
	v_readlane_b32 s52, v255, 13
	v_pk_mul_f32 v[8:9], v[8:9], v[16:17]
	v_readlane_b32 s53, v255, 14
	v_cvt_pk_bf16_f32 v3, v8, v9
	v_cvt_pk_bf16_f32 v4, v4, v5
	v_cvt_pk_bf16_f32 v5, v12, v13
	global_store_dwordx4 v[6:7], v[2:5], off
	s_cbranch_vccnz .LBB0_920
	s_andn2_b64 vcc, exec, s[4:5]
	s_cbranch_vccnz .LBB0_919
	s_barrier
	s_branch .LBB0_919
